# gate pre-activation scaling folded into the staged conv taps; padding keeps the hot loops at the same 64-byte alignment as the previous best
# speedup vs baseline: 1.0040x; 1.0040x over previous
; #define PG8_LAS __attribute__((address_space(3)))
; #define PG8_STAGE(bufoff, gbase, voff) do { _Pragma("unroll") for (int _i = 0; _i < 2; ++_i) \
;         __builtin_amdgcn_global_load_lds((const unsigned*)((const char*)(gbase) + (voff)[_i]), (PG8_LAS unsigned*)(lds + (bufoff) + ldsw + _i * 8192), 16, 0, 0); } while (0)
; #define PG8_WAIT_V(n) asm volatile("s_waitcnt vmcnt(" #n ")" ::: "memory")
; #define PG8_BAR __builtin_amdgcn_s_barrier()
; template <class Epi, class Sched, bool ALIGN_EPI = false, bool SP2 = false>
; __device__ __forceinline__ void gemm_phase(PG8_LAS unsigned char* lds, const Gemm g, const Sched& S, const Epi& E) {
;     ...
;         PG8_STAGE(PG8_SB(0, 0), cB, voffB); PG8_STAGE(PG8_SB(0, 1), cB + hstep, voffB); PG8_STAGE(PG8_SA(0, 0), cA, voffA); PG8_STAGE(PG8_SA(0, 1), cA + hstep, voffA);
;         if (wr == 1) PG8_BAR;
;         PG8_WAIT_V(2); PG8_BAR;
;         PG8_STAGE(PG8_SB(1, 0), cB + kstep, voffB); PG8_STAGE(PG8_SA(1, 0), cA + kstep, voffA); PG8_STAGE(PG8_SB(1, 1), cB + hstep + kstep, voffB);
;         PG8_WAIT_V(6); PG8_BAR;
;     } else {
;         PG8_STAGE(PG8_SB(0, 0), cB, voffB); PG8_STAGE(PG8_SA(0, 0), cA, voffA); PG8_STAGE(PG8_SB(0, 1), cB + hstep, voffB); PG8_STAGE(PG8_SA(0, 1), cA + hstep, voffA);
;         if (wr == 1) PG8_BAR;
;         PG8_WAIT_V(4); PG8_BAR;
;         PG8_STAGE(PG8_SB(1, 0), cB + kstep, voffB); PG8_STAGE(PG8_SA(1, 0), cA + kstep, voffA); PG8_STAGE(PG8_SB(1, 1), cB + hstep + kstep, voffB);
;         PG8_WAIT_V(6); PG8_BAR;
;     __device__ __forceinline__ void operator()(f32x4 (&acc)[2][2][4][2], const pg8::Unit& u, int wr, int wc, int fr, int fq) const {
;         const int colj = u.pn * 128 + wc * 32 + 8 * fq;
;         PG8_LAS unsigned char* wl = WL + (wr * 4 + wc) * 1024;
;         {
;             const int l = fq * 16 + fr, p = l >> 4, bj = (l >> 3) & 1, c4 = (l & 7) * 4;
;             const float* srcp = (p < 3 ? FW + p * NUP : FB) + bj * DFF + u.pn * 128 + wc * 32 + c4;
;             *(PG8_LAS f32x4*)(wl + l * 16) = *(const f32x4*)srcp;
.LBB0_739:
	s_add_u32 s28, s16, 0xa000000
	s_mov_b64 s[30:31], 0x80
	s_addc_u32 s29, s17, 0
	s_and_b32 s5, s5, 3
	s_add_i32 m0, s35, 0x18000
	v_lshl_add_u64 v[6:7], v[6:7], 0, s[30:31]
	s_sext_i32_i16 s66, s0
	s_lshl_b32 s0, s4, 13
	s_lshl_b32 s12, s5, 12
	s_waitcnt vmcnt(2)
	s_barrier
	global_load_lds_dwordx4 v[6:7], off
	v_lshl_add_u64 v[4:5], v[4:5], 0, s[30:31]
	s_add_i32 m0, s35, 0x1a000
	s_add_i32 s54, s35, 0x8000
	s_add_i32 s55, s35, 0xa000
	global_load_lds_dwordx4 v[4:5], off
	v_lshl_add_u64 v[0:1], v[0:1], 0, s[30:31]
	s_mov_b32 m0, s54
	s_add_u32 s6, s10, 0x40080
	global_load_lds_dwordx4 v[0:1], off
	v_lshl_add_u64 v[0:1], v[2:3], 0, s[30:31]
	s_mov_b32 m0, s55
	s_addc_u32 s7, s11, 0
	global_load_lds_dwordx4 v[0:1], off
	s_add_i32 m0, s35, 0x1c000
	v_lshl_add_u64 v[0:1], s[6:7], 0, v[132:133]
	global_load_lds_dwordx4 v[0:1], off
	v_lshl_add_u64 v[0:1], s[6:7], 0, v[128:129]
	s_add_i32 m0, s35, 0x1e000
	v_lshrrev_b32_e32 v14, 4, v152
	global_load_lds_dwordx4 v[0:1], off
	v_and_b32_e32 v169, 15, v152
	v_bfe_u32 v239, v152, 3, 1
	v_mul_u32_u24_e32 v239, 0x873823, v239
	v_sub_u32_e32 v239, 0xbfb8aa3b, v239
	s_nop 0
	s_nop 0
	s_nop 0
	s_nop 0
	s_nop 0
	s_nop 0
	s_nop 0
	s_nop 0
	s_nop 0
	s_nop 0
	v_and_b32_e32 v15, 3, v14
	v_lshlrev_b32_e32 v14, 4, v15
	s_waitcnt vmcnt(0)
	v_lshlrev_b32_e32 v18, 2, v169
	v_lshl_or_b32 v17, v169, 6, v14
	v_and_b32_e32 v19, 32, v18
	s_cmpk_lt_u32 s1, 0x100
	v_bitop3_b32 v4, v17, s0, v19 bitop3:0xde
	v_lshlrev_b32_e32 v0, 6, v152
	s_movk_i32 s0, 0x3c0
	v_lshlrev_b32_e32 v1, 2, v152
	s_cselect_b64 s[84:85], -1, 0
	s_lshl_b32 s24, s4, 12
	v_and_or_b32 v0, v0, s0, v14
	v_and_b32_e32 v1, 32, v1
	s_lshl_b32 s38, s5, 10
	v_lshl_or_b32 v187, s4, 6, v18
	s_lshl_b32 s57, s4, 2
	s_add_i32 s4, s24, 0
	v_bitop3_b32 v171, s12, v0, v1 bitop3:0xf6
	v_bfe_u32 v0, v152, 3, 1
	v_mul_u32_u24_e32 v1, 0x1600, v15
	s_add_i32 s4, s4, s38
	v_readlane_b32 s36, v253, 18
	v_mul_u32_u24_e32 v2, 0xb00, v0
	v_lshlrev_b32_e32 v0, 2, v1
	v_mov_b32_e32 v1, v133
	v_readlane_b32 s46, v253, 28
	v_readlane_b32 s47, v253, 29
	v_readlane_b32 s49, v253, 31
	v_readlane_b32 s48, v253, 30
	v_lshl_add_u64 v[0:1], s[46:47], 0, v[0:1]
	v_mov_b32_e32 v3, s49
	v_cmp_eq_u32_e32 vcc, 3, v15
	v_lshlrev_b32_e32 v2, 2, v2
	v_lshlrev_b32_e32 v5, 4, v169
	v_cndmask_b32_e32 v1, v1, v3, vcc
	v_mov_b32_e32 v3, s48
	v_cndmask_b32_e32 v0, v0, v3, vcc
	v_mov_b32_e32 v3, v133
	v_lshl_add_u64 v[0:1], v[0:1], 0, v[2:3]
	s_lshl_b32 s24, s5, 7
	v_lshl_add_u64 v[0:1], v[0:1], 0, s[24:25]
	v_and_b32_e32 v2, 0x70, v5
	v_lshl_add_u64 v[136:137], v[0:1], 0, v[2:3]
	v_add3_u32 v0, v13, v10, v12
	v_lshl_or_b32 v0, v0, 11, v8
	s_mov_b64 s[12:13], 0x40080
	v_add_u32_e32 v0, v0, v9
	v_mov_b32_e32 v1, v133
	v_lshl_add_u64 v[140:141], v[0:1], 0, s[12:13]
	v_add3_u32 v0, v11, v10, v12
	v_lshl_or_b32 v0, v0, 11, v8
	s_waitcnt vmcnt(6)
	s_add_i32 s4, s4, 0x20100
	v_add_u32_e32 v0, v0, v9
	v_lshlrev_b32_e32 v16, 3, v15
	v_lshlrev_b32_e32 v6, 5, v15
	v_cmp_eq_u32_e64 s[6:7], 0, v169
	v_readlane_b32 s38, v253, 20
	v_lshl_add_u32 v2, v15, 8, s4
	v_mov_b32_e32 v15, v133
	v_lshl_add_u64 v[142:143], v[0:1], 0, s[12:13]
	s_add_i32 s61, 0, 0x10000
	s_add_i32 s62, 0, 0x14000
	v_mbcnt_lo_u32_b32 v0, -1, 0
	v_lshl_or_b32 v186, s5, 5, v16
	s_movk_i32 s56, 0x1600
	v_cmp_ne_u32_e64 s[0:1], 0, v169
	v_cndmask_b32_e64 v188, 2, 0, s[6:7]
	v_cndmask_b32_e64 v189, 3, 1, s[6:7]
	s_add_i32 s58, s57, 8
	s_ashr_i32 s59, s80, 31
	s_mov_b32 s60, s80
	v_readlane_b32 s40, v253, 22
	v_readlane_b32 s42, v253, 24
	v_lshl_add_u64 v[138:139], s[20:21], 0, v[14:15]
	v_mov_b64_e32 v[144:145], 0xb00
	v_mov_b64_e32 v[146:147], 0xaff
	v_add_u32_e32 v190, s61, v171
	v_add_u32_e32 v191, s62, v171
	v_add_u32_e32 v192, 0, v4
	v_add_u32_e32 v193, v2, v5
	v_mbcnt_hi_u32_b32 v194, -1, v0
	s_mov_b32 s24, 0x3a800000
	s_mov_b32 s38, 0x358637bd
	s_mov_b32 s63, 0x800000
	s_movk_i32 s64, 0x2c00
	s_movk_i32 s65, 0x1000
	v_add_u32_e32 v195, s4, v6
	s_barrier
	v_readlane_b32 s37, v253, 19
	v_readlane_b32 s39, v253, 21
	v_readlane_b32 s41, v253, 23
	v_readlane_b32 s43, v253, 25
	v_readlane_b32 s44, v253, 26
	v_readlane_b32 s45, v253, 27
	v_readlane_b32 s50, v253, 32
	v_readlane_b32 s51, v253, 33
	s_branch .LBB0_742

; #define PG8_WAIT_V(n) asm volatile("s_waitcnt vmcnt(" #n ")" ::: "memory")
; #define PG8_BAR __builtin_amdgcn_s_barrier()
; template <class Epi, class Sched, bool ALIGN_EPI = false, bool SP2 = false>
; __device__ __forceinline__ void gemm_phase(PG8_LAS unsigned char* lds, const Gemm g, const Sched& S, const Epi& E) {
;     ...
;     PG8_WAIT_V(0);
;     if constexpr (!ALIGN_EPI) { if (wr == 0) PG8_BAR; }
;     PG8_BAR;
.LBB0_763:
	s_nop 0
	s_nop 0
	s_nop 0
	s_nop 0
	s_nop 0
	s_nop 0
	s_nop 0
	s_nop 0
	s_nop 0
	s_nop 0
	s_nop 0
	s_nop 0
	s_waitcnt vmcnt(0)
	s_barrier
